# LDS bank-conflict swizzle: mLSTM transposed K tile (KTs) column blocks XOR-swizzled by channel group, making the 32 ds_write_b16 per chunk conflict-free; reader base mirrored
# baseline (speedup 1.0000x reference)
; #define LAS __attribute__((address_space(3)))
; DI void mlstm_item(int j, int item, LAS unsigned char* lds) {
;     unsigned char* ws = WSP();
;     const int tid = tid_opaque(), wave = __builtin_amdgcn_readfirstlane(tid >> 6), lane = tid & 63, fr = lane & 15, fq = lane >> 4;
;     const int b = item >> 5, head = (item >> 3) & 3, d = (item >> 2) & 1, vq = item & 3;
;     LAS bf16_t* Qs = (LAS bf16_t*)lds; LAS bf16_t* KPs = Qs + 128 * 136; LAS bf16_t* KTs = KPs + 128 * 136;
;     LAS bf16_t* VTs = KTs + 128 * 136; LAS bf16_t* VWs = VTs + 48 * 136; LAS bf16_t* Cs = VWs + 48 * 136;
;     LAS float* lfs = (LAS float*)(Cs + 48 * 136); LAS float* ics = lfs + 128; LAS float* gs = ics + 128; LAS float* bcs = gs + 128;
;     LAS float* wss = bcs + 128; LAS float* ats = wss + 128; LAS float* scal = ats + 128;
;     const bf16_t* Pb = (const bf16_t*)(ws + EV_P); const float* Gt = (const float*)(ws + EV_G);
;     bf16_t* HB = (bf16_t*)(ws + EV_HB) + (size_t)d * M * 512;
;     const float fb = IN(13)[(j * 2 + d) * 4 + head];
;     const float scale = 0.08838834764831845f;
;     __syncthreads();
;     for (int e = tid; e < 48 * 136; e += NTHREADS) { const int r = e / 136; Cs[e] = 0; VWs[e] = 0; VTs[e] = (r == 32) ? (bf16_t)0x3F80 : (bf16_t)0; }
;     f32x4 Ct[3];
; #pragma unroll
;     for (int i = 0; i < 3; ++i) Ct[i] = (f32x4){0.f, 0.f, 0.f, 0.f};
;     float mst = 0.f;
;     const int prow_ = tid >> 2, pcs_ = tid & 3;
;     float pgi = 0.f, pgf = 0.f; u32x4 pq[4], pk[4], pv;
;     { if (tid < 128) { const int mr = b * T + tok_of(d, tid); pgi = Gt[(size_t)mr * 16 + d * 8 + head]; pgf = Gt[(size_t)mr * 16 + d * 8 + 4 + head]; }
;       const bf16_t* s0_ = Pb + (size_t)(b * T + tok_of(d, prow_)) * PW + head * 128;
; #pragma unroll
;       for (int i = 0; i < 4; ++i) { pq[i] = *(const u32x4*)(s0_ + pcs_ * 32 + i * 8); pk[i] = *(const u32x4*)(s0_ + 1024 + pcs_ * 32 + i * 8); }
;       pv = *(const u32x4*)(s0_ + 1536 + vq * 32 + pcs_ * 8); }
;     ...
;             for (int i = 0; i < 4; ++i) { const u32x4 k = pk[i]; *(LAS u32x4*)(KPs + row * 136 + cs * 32 + i * 8) = k;
;                 const int c0 = cs * 32 + i * 8;
;                 KTs[(c0 + 0) * 136 + row] = (bf16_t)(k.x & 0xffff); KTs[(c0 + 1) * 136 + row] = (bf16_t)(k.x >> 16);
;                 KTs[(c0 + 2) * 136 + row] = (bf16_t)(k.y & 0xffff); KTs[(c0 + 3) * 136 + row] = (bf16_t)(k.y >> 16);
.LBB0_523:
	s_or_b64 exec, exec, s[6:7]
	s_add_u32 s6, s2, 0xb400000
	s_addc_u32 s7, s3, 0
	s_mul_i32 s8, s11, 0x2200000
	v_ashrrev_i32_e32 v39, 2, v42
	s_add_u32 s12, s2, s8
	s_movk_i32 s2, 0xff
	s_addc_u32 s13, s3, 0
	v_cmp_lt_i32_e32 vcc, s2, v39
	s_cmp_eq_u32 s11, 0
	s_cselect_b64 s[42:43], -1, 0
	v_cndmask_b32_e32 v0, v253, v196, vcc
	v_sub_u32_e32 v0, v0, v39
	v_cndmask_b32_e64 v0, v0, v39, s[42:43]
	v_add_u32_e32 v0, s34, v0
	v_mov_b64_e32 v[2:3], s[6:7]
	v_and_b32_e32 v43, 3, v42
	v_mad_i64_i32 v[2:3], s[2:3], v0, s78, v[2:3]
	s_lshl_b32 s80, s80, 8
	v_lshl_add_u64 v[34:35], v[2:3], 0, s[80:81]
	v_lshlrev_b32_e32 v86, 6, v43
	v_mov_b32_e32 v87, v1
	v_lshl_add_u64 v[30:31], v[34:35], 0, v[86:87]
	global_load_dwordx4 v[2:5], v[30:31], off offset:48
	global_load_dwordx4 v[6:9], v[30:31], off offset:32
	global_load_dwordx4 v[10:13], v[30:31], off offset:16
	global_load_dwordx4 v[14:17], v[30:31], off
	global_load_dwordx4 v[18:21], v[30:31], off offset:2048
	global_load_dwordx4 v[22:25], v[30:31], off offset:2064
	global_load_dwordx4 v[26:29], v[30:31], off offset:2080
	s_nop 0
	global_load_dwordx4 v[30:33], v[30:31], off offset:2096
	s_lshl_b32 s2, s14, 5
	s_and_b32 s2, s2, 0x60
	s_lshl_b32 s8, s2, 1
	s_mov_b32 s9, s81
	v_lshl_add_u64 v[34:35], v[34:35], 0, s[8:9]
	v_lshlrev_b32_e32 v0, 4, v43
	v_lshl_add_u64 v[34:35], v[34:35], 0, v[0:1]
	global_load_dwordx4 v[34:37], v[34:35], off offset:3072
	s_cmp_lt_u32 s10, 64
	s_cselect_b64 s[26:27], -1, 0
	s_add_u32 s6, s6, s80
	s_addc_u32 s7, s7, 0
	s_ashr_i32 s3, s10, 2
	s_and_b32 s9, s3, -16
	v_and_b32_e32 v0, -4, v42
	s_mul_i32 s10, s9, 0x110
	v_and_b32_e32 v47, 15, v42
	s_movk_i32 s11, 0x110
	v_add_u32_e32 v101, 0x23910, v0
	v_mov_b32_e32 v0, s10
	v_mad_u32_u24 v0, v47, s11, v0
	v_and_b32_e32 v52, 48, v42
	v_bfi_b32 v103, -16, s3, v42
	v_add3_u32 v102, v0, v52, 16
	v_lshlrev_b32_e32 v0, 2, v103
	v_add_u32_e32 v104, 0x23b10, v0
	v_add_u32_e32 v108, 0x23710, v0
	v_lshlrev_b32_e32 v0, 2, v42
	v_add_u32_e32 v109, 0x23310, v0
	v_add_u32_e32 v110, 0x23110, v0
	v_add_u32_e32 v117, 0x23910, v0
	v_mov_b32_e32 v0, 0x1cb10
	v_lshl_add_u32 v118, v42, 1, v0
	v_lshl_add_u64 v[40:41], v[40:41], 2, s[4:5]
	v_lshlrev_b32_e32 v0, 2, v38
	v_and_b32_e32 v57, 64, v187
	v_lshl_add_u64 v[92:93], v[40:41], 0, v[0:1]
	v_add_u32_e32 v0, -1, v187
	v_cmp_lt_i32_e32 vcc, v0, v57
	v_writelane_b32 v255, s14, 36
	v_writelane_b32 v255, s6, 37
	v_cndmask_b32_e32 v0, v0, v187, vcc
	v_lshlrev_b32_e32 v120, 2, v0
	v_add_u32_e32 v0, -2, v187
	v_cmp_lt_i32_e32 vcc, v0, v57
	s_add_u32 s3, s12, s80
	v_writelane_b32 v255, s7, 38
	v_cndmask_b32_e32 v0, v0, v187, vcc
	v_lshlrev_b32_e32 v121, 2, v0
	v_add_u32_e32 v0, -4, v187
	v_cmp_lt_i32_e32 vcc, v0, v57
	s_addc_u32 s7, s13, 0
	s_add_u32 s6, s3, s8
	v_cndmask_b32_e32 v0, v0, v187, vcc
	v_lshlrev_b32_e32 v122, 2, v0
	v_add_u32_e32 v0, -8, v187
	v_cmp_lt_i32_e32 vcc, v0, v57
	v_bfe_u32 v50, v42, 4, 2
	s_addc_u32 s7, s7, 0
	v_cndmask_b32_e32 v0, v0, v187, vcc
	v_lshlrev_b32_e32 v123, 2, v0
	v_add_u32_e32 v0, -16, v187
	v_cmp_lt_i32_e32 vcc, v0, v57
	s_lshl_b32 s3, s9, 1
	s_mov_b32 s14, 0x8810
	v_cndmask_b32_e32 v0, v0, v187, vcc
	v_lshlrev_b32_e32 v124, 2, v0
	v_subrev_u32_e32 v0, 32, v187
	v_cmp_lt_i32_e32 vcc, v0, v57
	v_lshlrev_b32_e32 v88, 3, v50
	v_mul_lo_u32 v48, v103, s11
	v_cndmask_b32_e32 v0, v0, v187, vcc
	s_add_i32 s3, s3, 0x1fe10
	v_lshlrev_b32_e32 v125, 2, v0
	v_bfrev_b32_e32 v0, 0.5
	v_mul_u32_u24_e32 v51, 0x110, v47
	v_lshlrev_b32_e32 v54, 2, v50
	v_add3_u32 v106, v48, v88, s14
	v_or_b32_e32 v48, v57, v47
	v_lshl_add_u32 v47, v47, 1, s3
	v_lshl_or_b32 v126, v187, 2, v0
	v_mul_u32_u24_e32 v0, 0x2200, v43
	v_lshlrev_b32_e32 v38, 1, v39
	s_mov_b32 s3, 0x11010
	v_lshlrev_b32_e32 v127, 4, v43
	v_xor_b32_e32 v38, v38, v127
	v_add3_u32 v127, v0, v38, s3
	v_or_b32_e32 v38, 17, v54
	v_cmp_le_i32_e64 s[66:67], v38, v103
	v_or_b32_e32 v38, 18, v54
	v_cmp_le_i32_e64 s[68:69], v38, v103
	v_or_b32_e32 v38, 19, v54
	v_cmp_le_i32_e64 s[70:71], v38, v103
	v_or_b32_e32 v38, 32, v54
; #define LAS __attribute__((address_space(3)))
; DI unsigned pk2(float lo, float hi) { return f2bf(lo) | (f2bf(hi) << 16); }
; DI int tok_of(int d, int i) { if (i < LC) return d ? (LC - 1 - i) : i; return d ? (LC + SL - 1 - (i - LC)) : i; }
; DI void mlstm_item(int j, int item, LAS unsigned char* lds) {
;     ...
;         f32x4 s[8];
; #pragma unroll
;         for (int i = 0; i < 8; ++i) s[i] = (f32x4){0.f, 0.f, 0.f, 0.f};
;         mm16<8, 4>(Qs + wave * 16 * 136, 136, KPs, 136, s, fr, fq);
;         __syncthreads();
;         const int trow = wave * 16 + fr; const float at = ats[trow];
; #pragma unroll
;         for (int nt = 0; nt < 8; ++nt) { const f32x4 g4 = *(const LAS f32x4*)(gs + nt * 16 + fq * 4); float o[4];
; #pragma unroll
;             for (int e = 0; e < 4; ++e) { const int sc = nt * 16 + fq * 4 + e; const float w = __expf(fminf(g4[e] - at, 0.f)); o[e] = (sc <= trow) ? s[nt][e] * scale * w : 0.f; }
;             u32x2 w2; w2.x = pk2(o[0], o[1]); w2.y = pk2(o[2], o[3]);
;             *(LAS u32x2*)(KPs + trow * 136 + nt * 16 + fq * 4) = w2; }
;         __syncthreads();
;         f32x4 num[3], num2[3];
; #pragma unroll
;         for (int i = 0; i < 3; ++i) { num[i] = (f32x4){0.f, 0.f, 0.f, 0.f}; num2[i] = (f32x4){0.f, 0.f, 0.f, 0.f}; }
;         mm16<3, 4>(KPs + wave * 16 * 136, 136, VTs, 136, num, fr, fq);
;         mm16<3, 4>(Qs + wave * 16 * 136, 136, Cs, 136, num2, fr, fq);
;         {
;             const float rs = __shfl(num[2][0], fr), qn = __shfl(num2[2][0], fr);
;             const float iw = __expf(mst - at), mt = bcs[trow] + at;
;             const float den = fmaxf(fabsf(rs + iw * qn), __expf(-mt)); const float inv = 1.f / den;
;             const int mrow = b * T + tok_of(d, i0 + trow);
; #pragma unroll
;             for (int nt = 0; nt < 2; ++nt) { const f32x4 o = (num[nt] + num2[nt] * iw) * inv;
;                 u32x2 w2; w2.x = pk2(o[0], o[1]); w2.y = pk2(o[2], o[3]);
;                 *(u32x2*)(HB + (size_t)mrow * 512 + head * 128 + vq * 32 + nt * 16 + fq * 4) = w2; }
;         }
; #pragma unroll
;         for (int i = 0; i < 3; ++i) Ct[i] *= carry;
;         mm16<3, 4>(KTs + wave * 16 * 136, 136, VWs, 136, Ct, fr, fq);
	v_cmp_le_i32_e64 s[72:73], v38, v103
	v_or_b32_e32 v38, 33, v54
	v_cmp_le_i32_e64 s[74:75], v38, v103
	v_or_b32_e32 v38, 34, v54
	v_cmp_le_i32_e64 s[76:77], v38, v103
	v_or_b32_e32 v38, 35, v54
	v_cmp_le_i32_e64 s[78:79], v38, v103
	v_or_b32_e32 v38, 48, v54
	s_mov_b32 s25, s81
	v_cmp_le_i32_e64 s[80:81], v38, v103
	v_or_b32_e32 v38, 49, v54
	v_cmp_le_i32_e64 s[82:83], v38, v103
	v_or_b32_e32 v38, 50, v54
	v_cmp_le_i32_e64 s[84:85], v38, v103
	v_or_b32_e32 v38, 51, v54
	v_cmp_le_i32_e64 s[86:87], v38, v103
	v_or_b32_e32 v38, 64, v54
	v_cmp_le_i32_e64 s[88:89], v38, v103
	v_or_b32_e32 v38, 0x41, v54
	v_cmp_le_i32_e64 s[90:91], v38, v103
	v_or_b32_e32 v38, 0x42, v54
	v_cmp_le_i32_e64 s[92:93], v38, v103
	v_or_b32_e32 v38, 0x43, v54
	v_cmp_le_i32_e64 s[94:95], v38, v103
	v_or_b32_e32 v38, 0x50, v54
	v_mov_b32_e32 v89, v1
	v_cmp_le_i32_e64 s[96:97], v38, v103
	v_or_b32_e32 v38, 0x51, v54
	v_lshlrev_b32_e32 v107, 2, v48
	v_lshl_add_u64 v[48:49], s[6:7], 0, v[88:89]
	s_mov_b64 s[6:7], 0x17200000
	v_cmp_le_i32_e64 s[4:5], v38, v103
	v_or_b32_e32 v38, 0x52, v54
	v_lshl_add_u64 v[90:91], v[48:49], 0, s[6:7]
	v_cmp_le_i32_e64 s[6:7], v38, v103
	v_or_b32_e32 v38, 0x53, v54
	s_add_i32 s10, s10, 0x11010
	v_cmp_le_i32_e64 s[8:9], v38, v103
	v_or_b32_e32 v38, 0x60, v54
	v_mul_lo_u32 v87, v39, s11
	v_lshrrev_b32_e32 v89, 3, v42
	v_and_b32_e32 v89, 48, v89
	v_xor_b32_e32 v89, v89, v52
	v_add3_u32 v89, s10, v51, v89
	v_cmp_le_i32_e64 s[10:11], v38, v103
	v_or_b32_e32 v38, 0x61, v54
	v_mul_u32_u24_e32 v0, 0x440, v43
	v_cmp_le_i32_e64 s[12:13], v38, v103
	v_or_b32_e32 v38, 0x62, v54
	v_add3_u32 v100, v87, v86, s14
	v_add_lshl_u32 v0, v0, v39, 1
	v_cmp_le_i32_e64 s[14:15], v38, v103
	v_or_b32_e32 v38, 0x63, v54
	v_add_u32_e32 v128, 0x19810, v0
	v_add_u32_e32 v129, 0x1cb10, v0
	v_or_b32_e32 v0, 2, v54
	v_cmp_le_i32_e64 s[16:17], v38, v103
	v_or_b32_e32 v38, 0x70, v54
	s_lshl_b32 s24, s2, 1
	v_cmp_le_i32_e64 s[60:61], v0, v103
	v_or_b32_e32 v0, 3, v54
	v_cmp_le_i32_e64 s[18:19], v38, v103
	v_or_b32_e32 v38, 0x71, v54
	v_writelane_b32 v255, s24, 39
	v_and_b32_e32 v45, 63, v42
	v_cmp_le_i32_e64 s[62:63], v0, v103
	v_or_b32_e32 v0, 16, v54
	v_cmp_le_i32_e64 s[20:21], v38, v103
	v_or_b32_e32 v38, 0x72, v54
	v_writelane_b32 v255, s25, 40
	v_lshlrev_b32_e32 v44, 5, v43
	v_lshlrev_b32_e32 v46, 3, v43
	v_add_u32_e32 v53, 0x8810, v52
	v_add_u32_e32 v105, 0x23510, v52
	v_add_u32_e32 v55, 0x19810, v52
	v_add_u32_e32 v56, 0x1fe10, v52
	v_add_u32_e32 v48, 0x1cb10, v52
	v_lshlrev_b32_e32 v49, 3, v45
	v_cmp_le_i32_e64 s[22:23], v38, v103
	v_or_b32_e32 v52, 0x73, v54
	v_mul_u32_u24_e32 v38, 0x440, v50
	v_mul_u32_u24_e32 v40, 0x110, v0
	v_writelane_b32 v255, s26, 41
	s_mov_b32 s35, 0
	v_add_u32_e32 v111, 0x23110, v49
	v_add_u32_e32 v112, 0x23310, v49
	v_cmp_eq_u32_e64 s[44:45], 0, v45
	v_add_u32_e32 v113, 0x23710, v49
	v_add_u32_e32 v114, 0x23510, v49
	v_add_u32_e32 v115, 0x23b10, v49
	v_add_u32_e32 v116, 0x23910, v49
	v_add_u32_e32 v119, 0x80, v39
	v_cmp_gt_u32_e64 s[46:47], 2, v45
	v_cmp_gt_u32_e64 s[48:49], 4, v45
	v_cmp_gt_u32_e64 s[50:51], 8, v45
	v_cmp_gt_u32_e64 s[52:53], 16, v45
	v_cmp_gt_u32_e64 s[54:55], 32, v45
	v_cmp_le_i32_e64 s[56:57], v54, v103
	v_cmp_lt_i32_e64 s[58:59], v54, v103
	v_cmp_le_i32_e64 s[64:65], v0, v103
	v_add_u32_e32 v130, 0x80, v42
	v_sub_u32_e32 v131, 0xffffff80, v42
	v_sub_u32_e32 v132, 0, v103
	v_sub_u32_e32 v133, 0xffffff80, v39
	v_lshlrev_b32_e32 v0, 1, v44
	v_writelane_b32 v255, s27, 42
	v_lshlrev_b32_e32 v94, 1, v46
	v_add_u32_e32 v134, v53, v51
	v_add_u32_e32 v135, v55, v51
	v_add_u32_e32 v136, v56, v51
	v_add_u32_e32 v137, v48, v51
	v_add_u32_e32 v139, v47, v38
	v_add_u32_e32 v144, v47, v40
	v_mov_b32_e32 v38, 0
	v_mov_b32_e32 v39, v145
	v_mov_b32_e32 v40, v145
	v_mov_b32_e32 v41, v145
	v_mov_b32_e32 v42, 0
	v_mov_b32_e32 v43, v145
	v_mov_b32_e32 v44, v145
	v_mov_b32_e32 v45, v145
	v_mov_b32_e32 v46, 0
	v_mov_b32_e32 v47, v145
	v_mov_b32_e32 v48, v145
	v_mov_b32_e32 v49, v145
	v_cmp_le_i32_e64 s[24:25], v52, v103
	s_branch .LBB0_525
